# VWP
# baseline (speedup 1.0000x reference)
; __device__ __forceinline__ void attn_phase(const bf16_t* __restrict__ proj, const bf16_t* __restrict__ KC,
;                            const bf16_t* __restrict__ VCT, const bf16_t* __restrict__ VT,
;                            bf16_t* __restrict__ mixed) {
;     ...
;   for (int idx = blockIdx.x; idx < 512; idx += gridDim.x) {
;     int tid = threadIdx.x;
;     asm volatile("" : "+v"(tid));
;     const int w = __builtin_amdgcn_readfirstlane(tid >> 6), lane = tid & 63, c = lane & 15, quad = lane >> 4;
;     const int tl = c >> 2, r = c & 3;
;     const int bg = idx & 7, slot = idx >> 3, rnd = slot >> 5, qq = slot & 31;
;     const int ttile = (rnd == 0) ? 63 - qq : qq;
;     const int b = bg >> 2, g = bg & 3;
;     const int t0 = ttile * 64;
;     const int head = g * 4 + r;
;     int tok[2];
;     tok[0] = t0 + w * 8 + tl;
;     tok[1] = tok[0] + 4;
;     const size_t row0 = (size_t)b * SEQ + tok[0];
;     const int krow0 = tid >> 4, kch = tid & 15;
;     const int vrow0 = tid >> 3, vch = tid & 7;
;     const int ntile_c = (4 * ttile + 3 + 63) >> 6;
.LBB0_254:
	s_or_b64 exec, exec, s[8:9]
	s_cmpk_lt_i32 s2, 0x200
	s_mov_b64 s[8:9], s[0:1]
	s_cselect_b64 s[28:29], -1, 0
	s_cmpk_gt_i32 s2, 0x1ff
	s_barrier
	s_cbranch_scc1 .LBB0_347
	v_readfirstlane_b32 s30, v254
	s_lshr_b32 s30, s30, 8
	s_cmp_lg_u32 s30, 0
	s_cbranch_scc0 .Lprio0_skip
	s_setprio 1
.Lprio0_skip:
	s_load_dwordx2 s[30:31], s[8:9], 0x68
	v_writelane_b32 v255, s26, 0
	v_mbcnt_lo_u32_b32 v0, -1, 0
	v_mbcnt_hi_u32_b32 v189, -1, v0
	v_writelane_b32 v255, s27, 1
	s_waitcnt lgkmcnt(0)
	s_add_u32 s36, s30, 0x1f400000
	s_addc_u32 s37, s31, 0
	s_add_u32 s69, s30, 0x3b800000
	s_addc_u32 s72, s31, 0
	s_add_u32 s73, s30, 0x3b880000
	s_addc_u32 s74, s31, 0
	s_add_u32 s75, s30, 0x3a800000
	s_addc_u32 s76, s31, 0
	v_writelane_b32 v255, s82, 2
	s_add_u32 s38, s30, 0x2e800000
	v_and_b32_e32 v210, 64, v189
	v_writelane_b32 v255, s83, 3
	s_mov_b32 s26, s84
	s_movk_i32 s43, 0x1000
	s_mov_b32 s35, 0
	v_mov_b32_e32 v181, 0
	s_movk_i32 s47, 0x4000
	s_addc_u32 s39, s31, 0
	s_movk_i32 s77, 0x6000
	s_movk_i32 s78, 0x110
	s_add_i32 s79, 16, 0x21800
	s_movk_i32 s80, 0x90
	s_movk_i32 s81, 0x7a00
	s_mov_b64 s[40:41], 0x4000
	s_mov_b32 s42, 0x3e0293ee
	s_mov_b32 s82, 0xf149f2ca
	s_mov_b32 s83, 0xefa18f08
	s_movk_i32 s84, 0x7000
	s_mov_b64 s[44:45], 0x22800
	s_mov_b32 s85, 0x22000
	s_movk_i32 s86, 0x88
	s_movk_i32 s87, 0x48
	s_mov_b32 s88, 0x80000
	s_mov_b32 s89, 0xf4000
	s_mov_b32 s90, 0x1f5ed000
	s_mov_b32 s91, 0x1f6e1000
	s_mov_b32 s46, 0x41000000
	s_mov_b64 s[48:49], 0x1e8000
	s_mov_b64 s[50:51], 0x80
	s_mov_b32 s92, 0x26000
	s_mov_b64 s[52:53], 0x800000
	s_mov_b32 s93, 0x800000
	s_mov_b32 s94, 0x880000
	s_mov_b64 s[54:55], 0x6800
	s_mov_b64 s[56:57], 0x1000
	v_xor_b32_e32 v211, 1, v189
	v_add_u32_e32 v212, 64, v210
	v_xor_b32_e32 v213, 2, v189
	v_mov_b32_e32 v214, 0xf149f2ca
	v_mov_b32_e32 v215, 0x4e6e6b28
	v_mov_b32_e32 v216, 0xff61b1e6
	v_mov_b32_e32 v182, 1.0
	s_mov_b32 s95, s2
	s_branch .LBB0_257

; __device__ __forceinline__ unsigned xb_add(unsigned* p, unsigned v) { return __hip_atomic_fetch_add(p, v, __ATOMIC_RELAXED, __HIP_MEMORY_SCOPE_AGENT); }
; __device__ __forceinline__ void xcd_barrier(const XcdBarrier& b) {
;   asm volatile("s_waitcnt vmcnt(0)" ::: "memory");
;   __syncthreads();
;   if (threadIdx.x == 0) {
;     unsigned* bar = b.bar;
;     __builtin_amdgcn_s_waitcnt(0);
;     const unsigned old = xb_add(&bar[XB_XSUB(b.x)], 1u);
;     const unsigned gen = old / b.nloc;
;     if (old + 1u == (gen + 1u) * b.nloc) {
;       __builtin_amdgcn_fence(__ATOMIC_RELEASE, "agent");
;       asm volatile("s_waitcnt vmcnt(0)" ::: "memory");
;       const unsigned og = xb_add(&bar[XB_TOP], 1u);
;       const unsigned tg = og / b.nx;
;       if (og + 1u == (tg + 1u) * b.nx) xb_add(&bar[XB_TOPGEN], 1u);
.LBB0_347:
	s_setprio 0
	s_waitcnt vmcnt(0)
	s_barrier
	s_and_saveexec_b64 s[8:9], s[4:5]
	s_cbranch_execz .LBB0_384
	s_mov_b64 s[10:11], exec
	v_mbcnt_lo_u32_b32 v0, s10, 0
	v_mbcnt_hi_u32_b32 v0, s11, v0
	s_lshl_b32 s24, s84, 6
	s_mov_b32 s15, 0
	v_cmp_eq_u32_e32 vcc, 0, v0
	s_waitcnt vmcnt(0) expcnt(0) lgkmcnt(0)
	s_and_saveexec_b64 s[12:13], vcc
	s_cbranch_execz .LBB0_350
	s_add_i32 s14, s24, 0x500
	s_lshl_b64 s[14:15], s[14:15], 2
	s_add_u32 s14, s20, s14
	s_addc_u32 s15, s21, s15
	s_bcnt1_i32_b64 s10, s[10:11]
	v_mov_b32_e32 v1, 0
	v_mov_b32_e32 v2, s10
	global_atomic_add v1, v1, v2, s[14:15] sc0

; __device__ __forceinline__ void attn_phase(const bf16_t* __restrict__ proj, const bf16_t* __restrict__ KC,
;                            const bf16_t* __restrict__ VCT, const bf16_t* __restrict__ VT,
;                            bf16_t* __restrict__ mixed) {
;     ...
;   for (int idx = blockIdx.x; idx < 512; idx += gridDim.x) {
;     int tid = threadIdx.x;
;     asm volatile("" : "+v"(tid));
;     const int w = __builtin_amdgcn_readfirstlane(tid >> 6), lane = tid & 63, c = lane & 15, quad = lane >> 4;
;     const int tl = c >> 2, r = c & 3;
;     const int bg = idx & 7, slot = idx >> 3, rnd = slot >> 5, qq = slot & 31;
;     const int ttile = (rnd == 0) ? 63 - qq : qq;
;     const int b = bg >> 2, g = bg & 3;
;     const int t0 = ttile * 64;
;     const int head = g * 4 + r;
;     int tok[2];
;     tok[0] = t0 + w * 8 + tl;
;     tok[1] = tok[0] + 4;
;     const size_t row0 = (size_t)b * SEQ + tok[0];
;     const int krow0 = tid >> 4, kch = tid & 15;
;     const int vrow0 = tid >> 3, vch = tid & 7;
;     const int ntile_c = (4 * ttile + 3 + 63) >> 6;
.LBB0_590:
	s_or_b64 exec, exec, s[6:7]
	s_mov_b64 s[6:7], s[0:1]
	s_and_b64 vcc, exec, s[86:87]
	s_barrier
	s_cbranch_vccnz .LBB0_683
	v_readfirstlane_b32 s24, v254
	s_lshr_b32 s24, s24, 8
	s_cmp_lg_u32 s24, 0
	s_cbranch_scc0 .Lprio1_skip
	s_setprio 1
.Lprio1_skip:
	s_load_dwordx2 s[24:25], s[6:7], 0x68
	v_writelane_b32 v255, s86, 4
	v_mbcnt_lo_u32_b32 v0, -1, 0
	v_mbcnt_hi_u32_b32 v189, -1, v0
	v_writelane_b32 v255, s87, 5
	s_waitcnt lgkmcnt(0)
	s_add_u32 s28, s24, 0x1f400000
	s_addc_u32 s29, s25, 0
	s_add_u32 s45, s24, 0x3b800000
	s_addc_u32 s49, s25, 0
	s_add_u32 s73, s24, 0x3b880000
	s_addc_u32 s74, s25, 0
	s_add_u32 s75, s24, 0x3a800000
	s_addc_u32 s76, s25, 0
	v_writelane_b32 v255, s85, 0
	s_add_u32 s30, s24, 0x2e800000
	v_and_b32_e32 v252, 64, v189
	v_writelane_b32 v255, s84, 2
	s_movk_i32 s3, 0x1000
	s_mov_b32 s27, 0
	v_mov_b32_e32 v181, 0
	s_movk_i32 s19, 0x4000
	s_addc_u32 s31, s25, 0
	s_movk_i32 s77, 0x6000
	s_movk_i32 s78, 0x110
	s_add_i32 s79, 16, 0x21800
	s_movk_i32 s80, 0x90
	s_mov_b64 s[34:35], 0xe000
	s_mov_b64 s[36:37], 0x8080
	s_mov_b64 s[38:39], 0x8100
	s_mov_b64 s[40:41], 0x8180
	s_movk_i32 s81, 0x7a00
	s_mov_b64 s[42:43], 0x4000
	s_mov_b32 s44, 0x3e0293ee
	s_mov_b32 s82, 0xf149f2ca
	s_mov_b32 s83, 0xefa18f08
	s_movk_i32 s84, 0x7000
	s_mov_b64 s[46:47], 0x22800
	s_mov_b32 s85, 0x22000
	s_movk_i32 s86, 0x88
	s_movk_i32 s87, 0x48
	s_mov_b32 s88, 0x80000
	s_mov_b32 s89, 0xf4000
	s_mov_b32 s90, 0x1f5ed000
	s_mov_b32 s91, 0x1f6e1000
	s_mov_b32 s48, 0x41000000
	s_mov_b64 s[50:51], 0x1e8000
	s_mov_b64 s[52:53], 0x80
	s_mov_b32 s92, 0x26000
	s_mov_b64 s[54:55], 0x800000
	s_mov_b32 s93, 0x800000
	s_mov_b32 s94, 0x880000
	s_mov_b64 s[56:57], 0x6800
	s_mov_b64 s[58:59], 0x1000
	v_xor_b32_e32 v253, 1, v189
	v_add_u32_e32 v212, 64, v252
	v_xor_b32_e32 v213, 2, v189
	v_mov_b32_e32 v214, 0xf149f2ca
	v_mov_b32_e32 v215, 0x4e6e6b28
	v_mov_b32_e32 v216, 0xff61b1e6
	v_mov_b32_e32 v182, 1.0
	s_mov_b32 s95, s2
	s_branch .LBB0_593

; __device__ __forceinline__ unsigned xb_add(unsigned* p, unsigned v) { return __hip_atomic_fetch_add(p, v, __ATOMIC_RELAXED, __HIP_MEMORY_SCOPE_AGENT); }
; __device__ __forceinline__ void xcd_barrier(const XcdBarrier& b) {
;   asm volatile("s_waitcnt vmcnt(0)" ::: "memory");
;   __syncthreads();
;   if (threadIdx.x == 0) {
;     unsigned* bar = b.bar;
;     __builtin_amdgcn_s_waitcnt(0);
;     const unsigned old = xb_add(&bar[XB_XSUB(b.x)], 1u);
;     const unsigned gen = old / b.nloc;
;     if (old + 1u == (gen + 1u) * b.nloc) {
;       __builtin_amdgcn_fence(__ATOMIC_RELEASE, "agent");
;       asm volatile("s_waitcnt vmcnt(0)" ::: "memory");
;       const unsigned og = xb_add(&bar[XB_TOP], 1u);
;       const unsigned tg = og / b.nx;
;       if (og + 1u == (tg + 1u) * b.nx) xb_add(&bar[XB_TOPGEN], 1u);
.LBB0_683:
	s_setprio 0
	s_waitcnt vmcnt(0)
	s_barrier
	s_and_saveexec_b64 s[6:7], s[4:5]
	s_cbranch_execz .LBB0_720
	s_mov_b64 s[10:11], exec
	v_mbcnt_lo_u32_b32 v0, s10, 0
	v_mbcnt_hi_u32_b32 v0, s11, v0
	s_lshl_b32 s3, s84, 6
	s_mov_b32 s15, 0
	v_cmp_eq_u32_e32 vcc, 0, v0
	s_waitcnt vmcnt(0) expcnt(0) lgkmcnt(0)
	s_and_saveexec_b64 s[12:13], vcc
	s_cbranch_execz .LBB0_686
	s_add_i32 s14, s3, 0x500
	s_lshl_b64 s[8:9], s[14:15], 2
	s_add_u32 s8, s20, s8
	s_addc_u32 s9, s21, s9
	s_bcnt1_i32_b64 s10, s[10:11]
	v_mov_b32_e32 v1, 0
	v_mov_b32_e32 v2, s10
	global_atomic_add v1, v1, v2, s[8:9] sc0
